# HG1: per-run lower-bound pair loaded once (was per chunk with vmcnt(0) draining the previous chunk's stores); the drain now sits at the V staging writes
# speedup vs baseline: 1.0046x; 1.0046x over previous
; #define LAS __attribute__((address_space(3)))
; #define HG1_UNIT(R, J, U) do { const int combo_ = (R) / rps, blk_ = (R) % rps, s_ = combo_ >> 3, hd_ = combo_ & 7, p_ = blk_ * 8 + (J), cs_ = (hd_ & 1) ? ncs - 1 - p_ : p_; \
;         U = (((s_ * ncs + cs_) * 4 + (hd_ >> 1)) * 2) + (hd_ & 1); } while (0)
; DI void phase_hg1(const Ctx& c, LAS unsigned char* lds, int g, int l, const bf16* PROJ, bf16* ST, bf16* RT, float* RDEC, float* GC, bf16* KT1, bf16* QTB, int bid, int nb, int tid) {
;     ...
;     for (int r = bid; r < 256; r += nb) {
;       f32x4 Sloc[2][4];
; #pragma unroll
;       for (int a = 0; a < 2; ++a)
; #pragma unroll
;           for (int b = 0; b < 4; ++b) Sloc[a][b] = (f32x4){0.f, 0.f, 0.f, 0.f};
;       float lrun0 = 0.f, lrun1 = 0.f;
;       for (int jr = 0; jr < 8; ++jr) {
;         HG1_UNIT(r, jr, unit);
;         LAS unsigned char* lb_ = lds + (jr & 1) * HB;
;         LAS bf16* K1 = (LAS bf16*)lb_;
;         LAS bf16* Vimg = K1 + 64 * 136;
;         LAS float* tot = (LAS float*)(lb_ + 2 * 64 * 136 * 2);
;         LAS bf16* KS = (LAS bf16*)(lb_ + 2 * 64 * 136 * 2 + 4096);
;         LAS bf16* QS = KS + 64 * 136;
;         LAS float* asq = (LAS float*)(lb_ + 2 * 64 * 136 * 2 + 4096 + 2 * 64 * 136 * 2);
;         const int dir = unit & 1, h = (unit >> 1) & 3;
;         const float lb0 = LB[(dir * 2 + l) * 512 + h * 128 + 2 * k2], lb1 = LB[(dir * 2 + l) * 512 + h * 128 + 2 * k2 + 1];
.LBB0_265:
	s_abs_i32 s1, s86
	v_readlane_b32 s91, v254, 51
	s_mul_hi_u32 s18, s1, s91
	v_readlane_b32 s94, v254, 50
	s_mul_i32 s19, s18, s94
	s_ashr_i32 s85, s86, 31
	v_readlane_b32 s90, v254, 49
	s_sub_i32 s1, s1, s19
	s_xor_b32 s0, s85, s90
	s_add_i32 s19, s18, 1
	s_sub_i32 s20, s1, s94
	s_cmp_ge_u32 s1, s94
	s_cselect_b32 s18, s19, s18
	s_cselect_b32 s1, s20, s1
	s_add_i32 s19, s18, 1
	s_cmp_ge_u32 s1, s94
	s_cselect_b32 s1, s19, s18
	s_xor_b32 s1, s1, s0
	s_sub_i32 s20, s1, s0
	v_readlane_b32 s93, v254, 55
	s_ashr_i32 s1, s20, 3
	s_and_b32 s66, s20, 1
	v_readlane_b32 s92, v254, 38
	s_mul_i32 s0, s20, s93
	s_lshl_b32 s19, s1, s92
	s_lshl_b32 s1, s66, 10
	s_lshl_b32 s34, s20, 6
	s_sub_i32 s0, s86, s0
	s_or_b32 s1, s1, s33
	s_and_b32 s34, s34, 0x180
	s_mov_b32 s84, s86
	s_lshl_b32 s18, s0, 3
	s_and_b32 s0, s20, 7
	s_or_b32 s64, s1, s34
	s_add_i32 s86, s86, s87
	s_cmpk_lt_i32 s86, 0x100
	s_cselect_b64 s[80:81], -1, 0
	s_cmpk_gt_i32 s86, 0xff
	s_cselect_b64 s[82:83], -1, 0
	s_lshl_b64 s[34:35], s[84:85], 15
	v_readlane_b32 s26, v252, 28
	v_readlane_b32 s27, v252, 29
	s_add_u32 s34, s26, s34
	s_addc_u32 s35, s27, s35
	s_lshl_b64 s[62:63], s[84:85], 10
	s_cmp_eq_u32 s66, 0
	v_readlane_b32 s68, v254, 24
	v_lshl_add_u64 v[70:71], v[34:35], 0, s[62:63]
	s_cselect_b64 s[62:63], -1, 0
	v_or_b32_e32 v2, s64, v183
	v_mov_b32_e32 v3, v0
	v_readlane_b32 s74, v254, 30
	v_readlane_b32 s75, v254, 31
	s_and_b64 s[64:65], s[62:63], exec
	s_movk_i32 s26, 0x88
	v_lshl_add_u64 v[68:69], v[2:3], 2, s[74:75]
	global_load_dwordx2 v[162:163], v[68:69], off
	s_waitcnt vmcnt(0)
	v_cndmask_b32_e64 v2, v185, v184, s[62:63]
	s_cselect_b32 s64, 1, 6
	v_mul_lo_u32 v207, v2, s26
	v_or_b32_e32 v2, s64, v184
	s_cselect_b32 s64, 2, 5
	v_mul_lo_u32 v208, v2, s26
	v_or_b32_e32 v2, s64, v184
	v_mul_lo_u32 v209, v2, s26
	v_add_u32_e32 v2, s66, v203
	v_mul_lo_u32 v210, v2, s26
	v_subrev_u32_e32 v2, s66, v184
	s_cselect_b32 s64, 5, 2
	v_mul_lo_u32 v211, v2, s26
	v_or_b32_e32 v2, s64, v184
	s_cselect_b32 s64, 6, 1
	v_mul_lo_u32 v212, v2, s26
	v_or_b32_e32 v2, s64, v184
	v_mul_lo_u32 v213, v2, s26
	v_cndmask_b32_e64 v2, v184, v185, s[62:63]
	v_mul_lo_u32 v218, v2, s26
	v_cndmask_b32_e64 v2, 0, 1, s[6:7]
	v_cndmask_b32_e64 v3, 0, 1, s[4:5]
	v_cndmask_b32_e64 v2, v3, v2, s[62:63]
	v_lshl_add_u64 v[72:73], v[44:45], 1, s[34:35]
	v_lshl_add_u64 v[74:75], v[46:47], 1, s[34:35]
	v_lshl_add_u64 v[76:77], v[48:49], 1, s[34:35]
	v_lshl_add_u64 v[78:79], v[50:51], 1, s[34:35]
	v_lshl_add_u64 v[80:81], v[60:61], 1, s[34:35]
	v_lshl_add_u64 v[82:83], v[62:63], 1, s[34:35]
	v_lshl_add_u64 v[84:85], v[64:65], 1, s[34:35]
	v_lshl_add_u64 v[86:87], v[66:67], 1, s[34:35]
	s_abs_i32 s35, s86
	v_and_b32_e32 v2, 1, v2
	s_ashr_i32 s34, s86, 31
	s_mul_hi_u32 s85, s35, s91
	v_cmp_eq_u32_e64 s[64:65], 1, v2
	v_cndmask_b32_e64 v2, 0, 1, s[10:11]
	v_cndmask_b32_e64 v3, 0, 1, s[8:9]
	s_xor_b32 s34, s34, s90
	s_mul_i32 s90, s85, s94
	v_cndmask_b32_e64 v2, v3, v2, s[62:63]
	s_sub_i32 s35, s35, s90
	v_and_b32_e32 v2, 1, v2
	s_add_i32 s90, s85, 1
	s_sub_i32 s91, s35, s94
	v_cmp_eq_u32_e64 s[66:67], 1, v2
	v_cndmask_b32_e64 v2, 0, 1, s[14:15]
	v_cndmask_b32_e64 v3, 0, 1, s[12:13]
	s_cmp_ge_u32 s35, s94
	v_cndmask_b32_e64 v2, v3, v2, s[62:63]
	s_cselect_b32 s85, s90, s85
	v_readlane_b32 s69, v254, 25
	v_and_b32_e32 v2, 1, v2
	s_cselect_b32 s35, s91, s35
	s_add_i32 s90, s85, 1
	v_cmp_eq_u32_e64 s[68:69], 1, v2
	v_cndmask_b32_e64 v2, 0, 1, s[38:39]
	v_cndmask_b32_e64 v3, 0, 1, s[36:37]
	s_cmp_ge_u32 s35, s94
	v_cndmask_b32_e64 v2, v3, v2, s[62:63]
	s_cselect_b32 s35, s90, s85
	v_readlane_b32 s70, v254, 26
	v_readlane_b32 s71, v254, 27
	v_and_b32_e32 v2, 1, v2
	s_xor_b32 s35, s35, s34
	v_cmp_eq_u32_e64 s[70:71], 1, v2
	v_cndmask_b32_e64 v2, 0, 1, s[40:41]
	v_cndmask_b32_e64 v3, 0, 1, s[54:55]
	s_sub_i32 s34, s35, s34
	v_cndmask_b32_e64 v2, v3, v2, s[62:63]
	s_mul_i32 s35, s34, s93
	v_readlane_b32 s72, v254, 28
	v_readlane_b32 s73, v254, 29
	v_and_b32_e32 v2, 1, v2
	s_sub_i32 s35, s86, s35
	v_cmp_eq_u32_e64 s[72:73], 1, v2
	v_cndmask_b32_e64 v2, 0, 1, s[44:45]
	v_cndmask_b32_e64 v3, 0, 1, s[42:43]
	s_lshl_b32 s35, s35, 3
	v_cndmask_b32_e64 v2, v3, v2, s[62:63]
	s_not_b32 s91, s35
	v_readlane_b32 s26, v254, 53
	v_and_b32_e32 v2, 1, v2
	s_lshr_b32 s85, s34, 3
	s_and_b32 s90, s34, 1
	s_add_i32 s91, s26, s91
	v_cmp_eq_u32_e64 s[74:75], 1, v2
	v_cndmask_b32_e64 v2, 0, 1, s[48:49]
	v_cndmask_b32_e64 v3, 0, 1, s[46:47]
	s_cmp_eq_u32 s90, 0
	v_cndmask_b32_e64 v2, v3, v2, s[62:63]
	s_cselect_b32 s35, s35, s91
	s_lshl_b32 s85, s85, s92
	v_and_b32_e32 v2, 1, v2
	s_add_i32 s35, s35, s85
	v_cmp_eq_u32_e64 s[76:77], 1, v2
	v_cndmask_b32_e64 v2, 0, 1, s[52:53]
	v_cndmask_b32_e64 v3, 0, 1, s[50:51]
	s_lshl_b32 s35, s35, 3
	s_and_b32 s34, s34, 6
	v_readlane_b32 s26, v254, 56
	v_cndmask_b32_e64 v2, v3, v2, s[62:63]
	s_or_b32 s34, s35, s34
	s_mul_i32 s20, s26, s20
	v_readlane_b32 s26, v254, 54
	v_and_b32_e32 v2, 1, v2
	s_or_b32 s96, s34, s90
	s_add_i32 s20, s26, s20
	s_lshl_b32 s34, s84, 3
	v_mov_b32_e32 v88, 0
	s_mov_b32 s1, 0
	v_cmp_eq_u32_e64 s[78:79], 1, v2
	s_sub_i32 s34, s20, s34
	v_mov_b32_e32 v89, v88
	v_mov_b32_e32 v90, v88
	v_mov_b32_e32 v91, v88
	v_mov_b32_e32 v92, v88
	v_mov_b32_e32 v93, v88
	v_mov_b32_e32 v94, v88
	v_mov_b32_e32 v95, v88
	v_mov_b32_e32 v96, v88
	v_mov_b32_e32 v97, v88
	v_mov_b32_e32 v98, v88
	v_mov_b32_e32 v99, v88
	v_mov_b32_e32 v100, v88
	v_mov_b32_e32 v101, v88
	v_mov_b32_e32 v102, v88
	v_mov_b32_e32 v103, v88
	v_mov_b32_e32 v104, v88
	v_mov_b32_e32 v105, v88
	v_mov_b32_e32 v106, v88
	v_mov_b32_e32 v107, v88
	v_mov_b32_e32 v108, v88
	v_mov_b32_e32 v109, v88
	v_mov_b32_e32 v110, v88
	v_mov_b32_e32 v111, v88
	v_mov_b32_e32 v112, v88
	v_mov_b32_e32 v113, v88
	v_mov_b32_e32 v114, v88
	v_mov_b32_e32 v115, v88
	v_mov_b32_e32 v116, v88
	v_mov_b32_e32 v117, v88
	v_mov_b32_e32 v118, v88
	v_mov_b32_e32 v119, v88
	v_mov_b32_e32 v120, v88
	v_mov_b32_e32 v121, v88
	s_branch .LBB0_267

; #define LAS __attribute__((address_space(3)))
; DI float bflo(unsigned w) { return __uint_as_float(w << 16); }
; DI float bfhi(unsigned w) { return __uint_as_float(w & 0xffff0000u); }
; DI void phase_hg1(const Ctx& c, LAS unsigned char* lds, int g, int l, const bf16* PROJ, bf16* ST, bf16* RT, float* RDEC, float* GC, bf16* KT1, bf16* QTB, int bid, int nb, int tid) {
;     ...
;         const int dir = unit & 1, h = (unit >> 1) & 3;
;         const float lb0 = LB[(dir * 2 + l) * 512 + h * 128 + 2 * k2], lb1 = LB[(dir * 2 + l) * 512 + h * 128 + 2 * k2 + 1];
;         float pf0[8], pf1[8], fv0[8], fv1[8]; float p0 = 1.f, p1 = 1.f;
; #pragma unroll
;         for (int e = 0; e < 8; ++e) { const int tau_ = dir ? seg * 8 + 7 - e : seg * 8 + e; const unsigned zzv = *(const LAS unsigned*)(KS + tau_ * 136 + 2 * k2); qq[e] = *(const LAS unsigned*)(QS + tau_ * 136 + 2 * k2);
;             const float z0 = bflo(zzv), z1 = bfhi(zzv);
;             const float ez0 = __expf(-z0), ez1 = __expf(-z1), s0 = __builtin_amdgcn_rcpf(1.0f + ez0), s1_ = __builtin_amdgcn_rcpf(1.0f + ez1);
;             const float f0 = lb0 + (1.0f - lb0) * s0, f1 = lb1 + (1.0f - lb1) * s1_;
;             fv0[e] = f0; fv1[e] = f1; p0 *= f0; p1 *= f1; pf0[e] = p0; pf1[e] = p1; }
;         const float run0 = __builtin_amdgcn_logf(fmaxf(p0, 1e-37f)) * 0.69314718056f, run1 = __builtin_amdgcn_logf(fmaxf(p1, 1e-37f)) * 0.69314718056f;
;         tot[seg * 128 + 2 * k2] = run0; tot[seg * 128 + 2 * k2 + 1] = run1;
; #pragma unroll
;         for (int i = 0; i < 2; ++i) { const int ch = tid + i * NT, row = ch >> 4, sub = ch & 15; *(LAS u32x4*)(Vimg + row * 136 + sub * 8) = vch[i]; }
;         __syncthreads();
.LBB0_267:
	s_add_i32 s92, s18, s1
	s_bitcmp1_b32 s1, 0
	s_cselect_b32 s20, 0x12400, 0
	s_add_i32 s35, s20, 0
	v_lshl_add_u32 v134, v183, 1, s35
	v_lshl_add_u32 v5, v207, 1, v134
	ds_read2st64_b32 v[2:3], v5 offset0:152 offset1:220
	s_mov_b32 s20, 0x3f317218
	s_cmp_eq_u32 s1, 7
	s_cselect_b64 s[90:91], -1, 0
	s_waitcnt lgkmcnt(0)
	v_lshlrev_b32_e32 v122, 16, v2
	v_and_b32_e32 v2, 0xffff0000, v2
	v_mul_f32_e32 v2, 0xbfb8aa3b, v2
	v_mul_f32_e32 v122, 0xbfb8aa3b, v122
	v_exp_f32_e32 v2, v2
	v_exp_f32_e32 v122, v122
	s_mov_b64 s[84:85], -1
	s_and_b64 vcc, exec, s[90:91]
	v_add_f32_e32 v2, 1.0, v2
	v_add_f32_e32 v122, 1.0, v122
	v_rcp_f32_e32 v137, v2
	v_lshl_add_u32 v2, v208, 1, v134
	v_rcp_f32_e32 v136, v122
	ds_read2st64_b32 v[122:123], v2 offset0:152 offset1:220
	s_waitcnt lgkmcnt(0)
	v_lshlrev_b32_e32 v124, 16, v122
	v_and_b32_e32 v122, 0xffff0000, v122
	v_mul_f32_e32 v122, 0xbfb8aa3b, v122
	v_mul_f32_e32 v124, 0xbfb8aa3b, v124
	v_exp_f32_e32 v122, v122
	v_exp_f32_e32 v124, v124
	v_add_f32_e32 v122, 1.0, v122
	v_add_f32_e32 v124, 1.0, v124
	v_rcp_f32_e32 v139, v122
	v_lshl_add_u32 v122, v209, 1, v134
	v_rcp_f32_e32 v138, v124
	ds_read2st64_b32 v[124:125], v122 offset0:152 offset1:220
	s_waitcnt lgkmcnt(0)
	v_lshlrev_b32_e32 v126, 16, v124
	v_and_b32_e32 v124, 0xffff0000, v124
	v_mul_f32_e32 v124, 0xbfb8aa3b, v124
	v_mul_f32_e32 v126, 0xbfb8aa3b, v126
	v_exp_f32_e32 v124, v124
	v_exp_f32_e32 v126, v126
	v_add_f32_e32 v124, 1.0, v124
	v_add_f32_e32 v126, 1.0, v126
	v_rcp_f32_e32 v141, v124
	v_lshl_add_u32 v124, v210, 1, v134
	v_rcp_f32_e32 v140, v126
	ds_read2st64_b32 v[126:127], v124 offset0:152 offset1:220
	s_waitcnt lgkmcnt(0)
	v_lshlrev_b32_e32 v128, 16, v126
	v_and_b32_e32 v126, 0xffff0000, v126
	v_mul_f32_e32 v126, 0xbfb8aa3b, v126
	v_exp_f32_e32 v126, v126
	v_mul_f32_e32 v128, 0xbfb8aa3b, v128
	v_exp_f32_e32 v128, v128
	v_add_f32_e32 v126, 1.0, v126
	v_rcp_f32_e32 v143, v126
	v_lshl_add_u32 v126, v211, 1, v134
	v_add_f32_e32 v128, 1.0, v128
	v_add_u32_e32 v126, 64, v126
	v_rcp_f32_e32 v142, v128
	ds_read2st64_b32 v[128:129], v126 offset0:156 offset1:224
	s_waitcnt lgkmcnt(0)
	v_lshlrev_b32_e32 v130, 16, v128
	v_and_b32_e32 v128, 0xffff0000, v128
	v_mul_f32_e32 v128, 0xbfb8aa3b, v128
	v_mul_f32_e32 v130, 0xbfb8aa3b, v130
	v_exp_f32_e32 v128, v128
	v_exp_f32_e32 v130, v130
	v_mov_b32_e32 v172, v162
	v_mov_b32_e32 v173, v163
	v_pk_add_f32 v[174:175], v[172:173], 1.0 op_sel_hi:[1,0] neg_lo:[1,0] neg_hi:[1,0]
	v_add_f32_e32 v128, 1.0, v128
	v_add_f32_e32 v130, 1.0, v130
	v_rcp_f32_e32 v145, v128
	v_lshl_add_u32 v128, v212, 1, v134
	v_rcp_f32_e32 v144, v130
	ds_read2st64_b32 v[130:131], v128 offset0:152 offset1:220
	v_pk_fma_f32 v[152:153], v[174:175], v[138:139], v[172:173]
	v_pk_fma_f32 v[140:141], v[174:175], v[140:141], v[172:173]
	v_pk_fma_f32 v[142:143], v[174:175], v[142:143], v[172:173]
	v_pk_fma_f32 v[144:145], v[174:175], v[144:145], v[172:173]
	s_waitcnt lgkmcnt(0)
	v_lshlrev_b32_e32 v132, 16, v130
	v_and_b32_e32 v130, 0xffff0000, v130
	v_mul_f32_e32 v130, 0xbfb8aa3b, v130
	v_mul_f32_e32 v132, 0xbfb8aa3b, v132
	v_exp_f32_e32 v130, v130
	v_exp_f32_e32 v132, v132
	v_add_f32_e32 v130, 1.0, v130
	v_add_f32_e32 v132, 1.0, v132
	v_rcp_f32_e32 v147, v130
	v_lshl_add_u32 v130, v213, 1, v134
	v_rcp_f32_e32 v146, v132
	ds_read2st64_b32 v[132:133], v130 offset0:152 offset1:220
	v_pk_fma_f32 v[146:147], v[174:175], v[146:147], v[172:173]
	s_waitcnt lgkmcnt(0)
	v_lshlrev_b32_e32 v135, 16, v132
	v_and_b32_e32 v132, 0xffff0000, v132
	v_mul_f32_e32 v132, 0xbfb8aa3b, v132
	v_mul_f32_e32 v135, 0xbfb8aa3b, v135
	v_exp_f32_e32 v132, v132
	v_exp_f32_e32 v135, v135
	v_add_f32_e32 v132, 1.0, v132
	v_add_f32_e32 v135, 1.0, v135
	v_rcp_f32_e32 v149, v132
	v_lshl_add_u32 v132, v218, 1, v134
	v_rcp_f32_e32 v148, v135
	ds_read2st64_b32 v[134:135], v132 offset0:152 offset1:220
	v_pk_fma_f32 v[148:149], v[174:175], v[148:149], v[172:173]
	s_waitcnt lgkmcnt(0)
	v_lshlrev_b32_e32 v150, 16, v134
	v_and_b32_e32 v134, 0xffff0000, v134
	v_mul_f32_e32 v150, 0xbfb8aa3b, v150
	v_mul_f32_e32 v134, 0xbfb8aa3b, v134
	v_exp_f32_e32 v150, v150
	v_exp_f32_e32 v134, v134
	v_add_f32_e32 v150, 1.0, v150
	v_add_f32_e32 v134, 1.0, v134
	v_rcp_f32_e32 v150, v150
	v_rcp_f32_e32 v151, v134
	s_nop 0
	v_pk_fma_f32 v[170:171], v[174:175], v[150:151], v[172:173]
	v_pk_fma_f32 v[150:151], v[174:175], v[136:137], v[172:173]
	s_nop 0
	v_pk_mul_f32 v[154:155], v[150:151], v[152:153]
	s_nop 0
	v_pk_mul_f32 v[156:157], v[154:155], v[140:141]
	s_nop 0
	v_pk_mul_f32 v[164:165], v[156:157], v[142:143]
	s_nop 0
	v_pk_mul_f32 v[166:167], v[164:165], v[144:145]
	s_nop 0
	v_pk_mul_f32 v[168:169], v[166:167], v[146:147]
	s_nop 0
	v_pk_mul_f32 v[172:173], v[168:169], v[148:149]
	s_nop 0
	v_pk_mul_f32 v[174:175], v[172:173], v[170:171]
	s_nop 0
	v_max_f32_e32 v134, 0x2081cea, v174
	v_log_f32_e32 v136, v134
	v_max_f32_e32 v134, 0x2081cea, v175
	v_log_f32_e32 v137, v134
	v_lshlrev_b32_e32 v134, 2, v183
	v_add3_u32 v134, s35, v186, v134
	v_pk_mul_f32 v[180:181], v[136:137], s[20:21] op_sel_hi:[1,0]
	ds_write_b64 v134, v[180:181] offset:34816
	v_lshl_add_u32 v134, v187, 1, s35
	v_add_u32_e32 v136, v134, v190
	v_add_u32_e32 v134, v134, v191
	s_waitcnt vmcnt(0)
	ds_write_b128 v136, v[6:9] offset:17408
	ds_write_b128 v134, v[10:13] offset:17408
	s_waitcnt lgkmcnt(0)
	s_barrier
	s_cbranch_vccnz .LBB0_269
	s_add_i32 s20, s92, 1
	s_and_b64 s[84:85], s[62:63], exec
	s_cselect_b32 s20, s20, s34
	s_add_i32 s20, s20, s19
	s_lshl_b32 s20, s20, 3
	s_or_b32 s20, s20, s0
	s_mov_b64 s[84:85], 0
